# de-serialised out-proj and down-proj epilogues (all residual loads issued up front, SGPR row bases)
# speedup vs baseline: 1.0213x; 1.0052x over previous
; __device__ __forceinline__ unsigned cvt_pk_bf16(float lo, float hi) { unsigned r; asm volatile("v_cvt_pk_bf16_f32 %0, %1, %2" : "=v"(r) : "v"(lo), "v"(hi)); return r; }
;     __device__ __forceinline__ void operator()(const f32x4 (&acc)[2][2][4][2], const Unit& u, int wr, int wc, int fr, int fq) const {
;         const int row0 = u.pm * 256 + wr * 64 + fr, col0 = u.pn * 256 + wc * 32 + 8 * fq, b = (u.pm * 256) >> 12;
;         f32x4 g[2][2];
; #pragma unroll
;         for (int bj = 0; bj < 2; ++bj)
; #pragma unroll
;             for (int n = 0; n < 2; ++n) g[bj][n] = *(const f32x4*)(gate + b * MODW + col0 + 128 * bj + 4 * n);
; #pragma unroll
;         for (int ai = 0; ai < 2; ++ai)
; #pragma unroll
;             for (int m = 0; m < 4; ++m) { const int row = row0 + 128 * ai + 16 * m;
; #pragma unroll
;                 for (int bj = 0; bj < 2; ++bj) { const size_t off = (size_t)row * DM + col0 + 128 * bj;
;                     const f32x4 a0 = *(const f32x4*)(x + off) + g[bj][0] * acc[ai][bj][m][0], a1 = *(const f32x4*)(x + off + 4) + g[bj][1] * acc[ai][bj][m][1];
;                     u32x4 w; w.x = cvt_pk_bf16(a0.x, a0.y); w.y = cvt_pk_bf16(a0.z, a0.w); w.z = cvt_pk_bf16(a1.x, a1.y); w.w = cvt_pk_bf16(a1.z, a1.w);
;                     *(u32x4*)(x1b + off) = w; } }
.LBB0_820:
	s_lshr_b32 s23, s30, 4
	s_mul_i32 s34, s23, 0x1800
	s_ashr_i32 s35, s34, 31
	v_lshl_add_u32 v164, s30, 8, v166
	v_lshl_or_b32 v162, s52, 8, v168
	s_lshl_b64 s[34:35], s[34:35], 2
	s_add_u32 s34, s46, s34
	s_addc_u32 s35, s47, s35
	v_lshlrev_b32_e32 v163, 2, v162
	v_lshl_add_u32 v160, v164, 10, v162
	global_load_dwordx4 v[136:139], v163, s[34:35]
	global_load_dwordx4 v[140:143], v163, s[34:35] offset:16
	global_load_dwordx4 v[132:135], v163, s[34:35] offset:512
	global_load_dwordx4 v[128:131], v163, s[34:35] offset:528
	v_lshlrev_b32_e32 v161, 2, v160
	v_lshlrev_b32_e32 v165, 1, v160
	s_andn2_b64 vcc, exec, s[6:7]
	s_mov_b64 s[6:7], -1
	s_mov_b64 s[98:99], s[2:3]
	global_load_dwordx4 v[172:175], v161, s[98:99]
	global_load_dwordx4 v[176:179], v161, s[98:99] offset:16
	global_load_dwordx4 v[180:183], v161, s[98:99] offset:512
	global_load_dwordx4 v[184:187], v161, s[98:99] offset:528
	s_add_u32 s98, s2, 0x10000
	s_addc_u32 s99, s3, 0
	global_load_dwordx4 v[188:191], v161, s[98:99]
	global_load_dwordx4 v[192:195], v161, s[98:99] offset:16
	global_load_dwordx4 v[196:199], v161, s[98:99] offset:512
	global_load_dwordx4 v[200:203], v161, s[98:99] offset:528
	s_add_u32 s98, s2, 0x20000
	s_addc_u32 s99, s3, 0
	global_load_dwordx4 v[204:207], v161, s[98:99]
	global_load_dwordx4 v[208:211], v161, s[98:99] offset:16
	global_load_dwordx4 v[220:223], v161, s[98:99] offset:512
	global_load_dwordx4 v[224:227], v161, s[98:99] offset:528
	s_add_u32 s98, s2, 0x30000
	s_addc_u32 s99, s3, 0
	global_load_dwordx4 v[228:231], v161, s[98:99]
	global_load_dwordx4 v[232:235], v161, s[98:99] offset:16
	global_load_dwordx4 v[236:239], v161, s[98:99] offset:512
	global_load_dwordx4 v[240:243], v161, s[98:99] offset:528
	s_waitcnt vmcnt(14)
	v_pk_fma_f32 v[124:125], v[124:125], v[136:137], v[172:173]
	v_pk_fma_f32 v[244:245], v[122:123], v[142:143], v[178:179]
	v_pk_fma_f32 v[122:123], v[120:121], v[140:141], v[176:177]
	v_pk_fma_f32 v[126:127], v[126:127], v[138:139], v[174:175]
	s_mov_b64 s[100:101], s[8:9]
	v_cvt_pk_bf16_f32 v120, v124, v125
	v_cvt_pk_bf16_f32 v121, v126, v127
	v_cvt_pk_bf16_f32 v122, v122, v123
	v_cvt_pk_bf16_f32 v123, v244, v245
	global_store_dwordx4 v165, v[120:123], s[100:101]
	s_add_u32 s98, s2, 0x80000
	s_addc_u32 s99, s3, 0
	global_load_dwordx4 v[120:123], v161, s[98:99]
	global_load_dwordx4 v[124:127], v161, s[98:99] offset:16
	s_waitcnt vmcnt(15)
	v_pk_fma_f32 v[116:117], v[116:117], v[132:133], v[180:181]
	v_pk_fma_f32 v[244:245], v[114:115], v[130:131], v[186:187]
	v_pk_fma_f32 v[114:115], v[112:113], v[128:129], v[184:185]
	v_pk_fma_f32 v[118:119], v[118:119], v[134:135], v[182:183]
	v_cvt_pk_bf16_f32 v112, v116, v117
	v_cvt_pk_bf16_f32 v113, v118, v119
	v_cvt_pk_bf16_f32 v114, v114, v115
	v_cvt_pk_bf16_f32 v115, v244, v245
	global_store_dwordx4 v165, v[112:115], s[100:101] offset:256
	s_nop 0
	global_load_dwordx4 v[112:115], v161, s[98:99] offset:512
	global_load_dwordx4 v[116:119], v161, s[98:99] offset:528
	s_waitcnt vmcnt(16)
	v_pk_fma_f32 v[108:109], v[108:109], v[136:137], v[188:189]
	v_pk_fma_f32 v[244:245], v[106:107], v[142:143], v[194:195]
	v_pk_fma_f32 v[106:107], v[104:105], v[140:141], v[192:193]
	v_pk_fma_f32 v[110:111], v[110:111], v[138:139], v[190:191]
	s_add_u32 s100, s8, 0x8000
	s_addc_u32 s101, s9, 0
	v_cvt_pk_bf16_f32 v104, v108, v109
	v_cvt_pk_bf16_f32 v105, v110, v111
	v_cvt_pk_bf16_f32 v106, v106, v107
	v_cvt_pk_bf16_f32 v107, v244, v245
	global_store_dwordx4 v165, v[104:107], s[100:101]
	s_add_u32 s98, s2, 0x90000
	s_addc_u32 s99, s3, 0
	global_load_dwordx4 v[104:107], v161, s[98:99]
	global_load_dwordx4 v[108:111], v161, s[98:99] offset:16
	s_waitcnt vmcnt(17)
	v_pk_fma_f32 v[100:101], v[100:101], v[132:133], v[196:197]
	v_pk_fma_f32 v[244:245], v[98:99], v[130:131], v[202:203]
	v_pk_fma_f32 v[98:99], v[96:97], v[128:129], v[200:201]
	v_pk_fma_f32 v[102:103], v[102:103], v[134:135], v[198:199]
	v_cvt_pk_bf16_f32 v96, v100, v101
	v_cvt_pk_bf16_f32 v97, v102, v103
	v_cvt_pk_bf16_f32 v98, v98, v99
	v_cvt_pk_bf16_f32 v99, v244, v245
	global_store_dwordx4 v165, v[96:99], s[100:101] offset:256
	s_nop 0
	global_load_dwordx4 v[96:99], v161, s[98:99] offset:512
	global_load_dwordx4 v[100:103], v161, s[98:99] offset:528
	s_waitcnt vmcnt(18)
	v_pk_fma_f32 v[92:93], v[92:93], v[136:137], v[204:205]
	v_pk_fma_f32 v[244:245], v[90:91], v[142:143], v[210:211]
	v_pk_fma_f32 v[90:91], v[88:89], v[140:141], v[208:209]
	v_pk_fma_f32 v[94:95], v[94:95], v[138:139], v[206:207]
	s_add_u32 s100, s8, 0x10000
	s_addc_u32 s101, s9, 0
	v_cvt_pk_bf16_f32 v88, v92, v93
	v_cvt_pk_bf16_f32 v89, v94, v95
	v_cvt_pk_bf16_f32 v90, v90, v91
	v_cvt_pk_bf16_f32 v91, v244, v245
	global_store_dwordx4 v165, v[88:91], s[100:101]
	s_add_u32 s98, s2, 0xa0000
	s_addc_u32 s99, s3, 0
	global_load_dwordx4 v[88:91], v161, s[98:99]
	global_load_dwordx4 v[92:95], v161, s[98:99] offset:16
	s_waitcnt vmcnt(19)
	v_pk_fma_f32 v[84:85], v[84:85], v[132:133], v[220:221]
	v_pk_fma_f32 v[244:245], v[82:83], v[130:131], v[226:227]
	v_pk_fma_f32 v[82:83], v[80:81], v[128:129], v[224:225]
	v_pk_fma_f32 v[86:87], v[86:87], v[134:135], v[222:223]
	v_cvt_pk_bf16_f32 v80, v84, v85
	v_cvt_pk_bf16_f32 v81, v86, v87
	v_cvt_pk_bf16_f32 v82, v82, v83
	v_cvt_pk_bf16_f32 v83, v244, v245
	global_store_dwordx4 v165, v[80:83], s[100:101] offset:256
	s_nop 0
	global_load_dwordx4 v[80:83], v161, s[98:99] offset:512
	global_load_dwordx4 v[84:87], v161, s[98:99] offset:528
	s_waitcnt vmcnt(20)
; __device__ __forceinline__ unsigned cvt_pk_bf16(float lo, float hi) { unsigned r; asm volatile("v_cvt_pk_bf16_f32 %0, %1, %2" : "=v"(r) : "v"(lo), "v"(hi)); return r; }
;     __device__ __forceinline__ void operator()(const f32x4 (&acc)[2][2][4][2], const Unit& u, int wr, int wc, int fr, int fq) const {
;     ...
;         for (int ai = 0; ai < 2; ++ai)
; #pragma unroll
;             for (int m = 0; m < 4; ++m) { const int row = row0 + 128 * ai + 16 * m;
; #pragma unroll
;                 for (int bj = 0; bj < 2; ++bj) { const size_t off = (size_t)row * DM + col0 + 128 * bj;
;                     const f32x4 a0 = *(const f32x4*)(x + off) + g[bj][0] * acc[ai][bj][m][0], a1 = *(const f32x4*)(x + off + 4) + g[bj][1] * acc[ai][bj][m][1];
;                     u32x4 w; w.x = cvt_pk_bf16(a0.x, a0.y); w.y = cvt_pk_bf16(a0.z, a0.w); w.z = cvt_pk_bf16(a1.x, a1.y); w.w = cvt_pk_bf16(a1.z, a1.w);
;                     *(u32x4*)(x1b + off) = w; } }
	v_pk_fma_f32 v[76:77], v[76:77], v[136:137], v[228:229]
	v_pk_fma_f32 v[244:245], v[74:75], v[142:143], v[234:235]
	v_pk_fma_f32 v[74:75], v[72:73], v[140:141], v[232:233]
	v_pk_fma_f32 v[78:79], v[78:79], v[138:139], v[230:231]
	s_add_u32 s100, s8, 0x18000
	s_addc_u32 s101, s9, 0
	v_cvt_pk_bf16_f32 v72, v76, v77
	v_cvt_pk_bf16_f32 v73, v78, v79
	v_cvt_pk_bf16_f32 v74, v74, v75
	v_cvt_pk_bf16_f32 v75, v244, v245
	global_store_dwordx4 v165, v[72:75], s[100:101]
	s_add_u32 s98, s2, 0xb0000
	s_addc_u32 s99, s3, 0
	global_load_dwordx4 v[72:75], v161, s[98:99]
	global_load_dwordx4 v[76:79], v161, s[98:99] offset:16
	s_waitcnt vmcnt(21)
	v_pk_fma_f32 v[68:69], v[68:69], v[132:133], v[236:237]
	v_pk_fma_f32 v[244:245], v[66:67], v[130:131], v[242:243]
	v_pk_fma_f32 v[66:67], v[64:65], v[128:129], v[240:241]
	v_pk_fma_f32 v[70:71], v[70:71], v[134:135], v[238:239]
	v_cvt_pk_bf16_f32 v64, v68, v69
	v_cvt_pk_bf16_f32 v65, v70, v71
	v_cvt_pk_bf16_f32 v66, v66, v67
	v_cvt_pk_bf16_f32 v67, v244, v245
	global_store_dwordx4 v165, v[64:67], s[100:101] offset:256
	s_nop 0
	global_load_dwordx4 v[64:67], v161, s[98:99] offset:512
	global_load_dwordx4 v[68:71], v161, s[98:99] offset:528
	s_waitcnt vmcnt(21)
	v_pk_fma_f32 v[60:61], v[60:61], v[136:137], v[120:121]
	v_pk_fma_f32 v[244:245], v[58:59], v[142:143], v[126:127]
	v_pk_fma_f32 v[58:59], v[56:57], v[140:141], v[124:125]
	v_pk_fma_f32 v[62:63], v[62:63], v[138:139], v[122:123]
	s_add_u32 s100, s8, 0x40000
	s_addc_u32 s101, s9, 0
	v_cvt_pk_bf16_f32 v56, v60, v61
	v_cvt_pk_bf16_f32 v57, v62, v63
	v_cvt_pk_bf16_f32 v58, v58, v59
	v_cvt_pk_bf16_f32 v59, v244, v245
	global_store_dwordx4 v165, v[56:59], s[100:101]
	s_waitcnt vmcnt(19)
	v_pk_fma_f32 v[52:53], v[52:53], v[132:133], v[112:113]
	v_pk_fma_f32 v[244:245], v[50:51], v[130:131], v[118:119]
	v_pk_fma_f32 v[50:51], v[48:49], v[128:129], v[116:117]
	v_pk_fma_f32 v[54:55], v[54:55], v[134:135], v[114:115]
	v_cvt_pk_bf16_f32 v48, v52, v53
	v_cvt_pk_bf16_f32 v49, v54, v55
	v_cvt_pk_bf16_f32 v50, v50, v51
	v_cvt_pk_bf16_f32 v51, v244, v245
	global_store_dwordx4 v165, v[48:51], s[100:101] offset:256
	s_waitcnt vmcnt(17)
	v_pk_fma_f32 v[44:45], v[44:45], v[136:137], v[104:105]
	v_pk_fma_f32 v[244:245], v[42:43], v[142:143], v[110:111]
	v_pk_fma_f32 v[42:43], v[40:41], v[140:141], v[108:109]
	v_pk_fma_f32 v[46:47], v[46:47], v[138:139], v[106:107]
	s_add_u32 s100, s8, 0x48000
	s_addc_u32 s101, s9, 0
	v_cvt_pk_bf16_f32 v40, v44, v45
	v_cvt_pk_bf16_f32 v41, v46, v47
	v_cvt_pk_bf16_f32 v42, v42, v43
	v_cvt_pk_bf16_f32 v43, v244, v245
	global_store_dwordx4 v165, v[40:43], s[100:101]
	s_waitcnt vmcnt(15)
	v_pk_fma_f32 v[36:37], v[36:37], v[132:133], v[96:97]
	v_pk_fma_f32 v[244:245], v[34:35], v[130:131], v[102:103]
	v_pk_fma_f32 v[34:35], v[32:33], v[128:129], v[100:101]
	v_pk_fma_f32 v[38:39], v[38:39], v[134:135], v[98:99]
	v_cvt_pk_bf16_f32 v32, v36, v37
	v_cvt_pk_bf16_f32 v33, v38, v39
	v_cvt_pk_bf16_f32 v34, v34, v35
	v_cvt_pk_bf16_f32 v35, v244, v245
	global_store_dwordx4 v165, v[32:35], s[100:101] offset:256
	s_waitcnt vmcnt(13)
	v_pk_fma_f32 v[28:29], v[28:29], v[136:137], v[88:89]
	v_pk_fma_f32 v[244:245], v[26:27], v[142:143], v[94:95]
	v_pk_fma_f32 v[26:27], v[24:25], v[140:141], v[92:93]
	v_pk_fma_f32 v[30:31], v[30:31], v[138:139], v[90:91]
	s_add_u32 s100, s8, 0x50000
	s_addc_u32 s101, s9, 0
	v_cvt_pk_bf16_f32 v24, v28, v29
	v_cvt_pk_bf16_f32 v25, v30, v31
	v_cvt_pk_bf16_f32 v26, v26, v27
	v_cvt_pk_bf16_f32 v27, v244, v245
	global_store_dwordx4 v165, v[24:27], s[100:101]
	s_waitcnt vmcnt(11)
	v_pk_fma_f32 v[20:21], v[20:21], v[132:133], v[80:81]
	v_pk_fma_f32 v[244:245], v[18:19], v[130:131], v[86:87]
	v_pk_fma_f32 v[18:19], v[16:17], v[128:129], v[84:85]
	v_pk_fma_f32 v[22:23], v[22:23], v[134:135], v[82:83]
	v_cvt_pk_bf16_f32 v16, v20, v21
	v_cvt_pk_bf16_f32 v17, v22, v23
	v_cvt_pk_bf16_f32 v18, v18, v19
	v_cvt_pk_bf16_f32 v19, v244, v245
	global_store_dwordx4 v165, v[16:19], s[100:101] offset:256
	s_waitcnt vmcnt(9)
	v_pk_fma_f32 v[12:13], v[12:13], v[136:137], v[72:73]
	v_pk_fma_f32 v[244:245], v[10:11], v[142:143], v[78:79]
	v_pk_fma_f32 v[10:11], v[8:9], v[140:141], v[76:77]
	v_pk_fma_f32 v[14:15], v[14:15], v[138:139], v[74:75]
	s_add_u32 s100, s8, 0x58000
	s_addc_u32 s101, s9, 0
	v_cvt_pk_bf16_f32 v8, v12, v13
	v_cvt_pk_bf16_f32 v9, v14, v15
	v_cvt_pk_bf16_f32 v10, v10, v11
	v_cvt_pk_bf16_f32 v11, v244, v245
	global_store_dwordx4 v165, v[8:11], s[100:101]
	s_waitcnt vmcnt(7)
	v_pk_fma_f32 v[4:5], v[4:5], v[132:133], v[64:65]
	v_pk_fma_f32 v[244:245], v[2:3], v[130:131], v[70:71]
	v_pk_fma_f32 v[2:3], v[0:1], v[128:129], v[68:69]
	v_pk_fma_f32 v[6:7], v[6:7], v[134:135], v[66:67]
	v_cvt_pk_bf16_f32 v0, v4, v5
	v_cvt_pk_bf16_f32 v1, v6, v7
	v_cvt_pk_bf16_f32 v2, v2, v3
	v_cvt_pk_bf16_f32 v3, v244, v245
	global_store_dwordx4 v165, v[0:3], s[100:101] offset:256
	s_cbranch_vccnz .LBB0_809
	s_andn2_b64 vcc, exec, s[4:5]
	s_cbranch_vccnz .LBB0_808
	s_barrier
	s_branch .LBB0_808

;     __device__ __forceinline__ void operator()(const f32x4 (&acc)[2][2][4][2], const Unit& u, int wr, int wc, int fr, int fq) const {
;         const int row0 = u.pm * 256 + wr * 64 + fr, col0 = u.pn * 256 + wc * 32 + 8 * fq, b = (u.pm * 256) >> 12;
;         f32x4 g[2][2];
; #pragma unroll
;         for (int bj = 0; bj < 2; ++bj)
; #pragma unroll
;             for (int n = 0; n < 2; ++n) g[bj][n] = *(const f32x4*)(gate + b * MODW + col0 + 128 * bj + 4 * n);
; #pragma unroll
;         for (int ai = 0; ai < 2; ++ai)
; #pragma unroll
;             for (int m = 0; m < 4; ++m) { const int row = row0 + 128 * ai + 16 * m;
; #pragma unroll
;                 for (int bj = 0; bj < 2; ++bj) { const size_t off = (size_t)row * DM + col0 + 128 * bj;
;                     const u32x4 w = *(const u32x4*)(x1b + off);
;                     const f32x4 x0 = (f32x4){__uint_as_float(w.x << 16), __uint_as_float(w.x & 0xffff0000u), __uint_as_float(w.y << 16), __uint_as_float(w.y & 0xffff0000u)};
;                     const f32x4 x1 = (f32x4){__uint_as_float(w.z << 16), __uint_as_float(w.z & 0xffff0000u), __uint_as_float(w.w << 16), __uint_as_float(w.w & 0xffff0000u)};
;                     *(f32x4*)(out + off) = x0 + g[bj][0] * acc[ai][bj][m][0]; *(f32x4*)(out + off + 4) = x1 + g[bj][1] * acc[ai][bj][m][1]; } }
.LBB0_1078:
	v_lshl_add_u32 v164, s51, 8, v166
	v_lshl_or_b32 v162, s52, 8, v168
	s_lshr_b32 s24, s51, 4
	s_mulk_i32 s24, 0x1800
	s_ashr_i32 s25, s24, 31
	s_lshl_b64 s[24:25], s[24:25], 2
	s_add_u32 s24, s43, s24
	s_addc_u32 s25, s44, s25
	v_lshlrev_b32_e32 v163, 2, v162
	v_lshl_add_u32 v160, v164, 10, v162
	global_load_dwordx4 v[132:135], v163, s[24:25]
	global_load_dwordx4 v[128:131], v163, s[24:25] offset:16
	global_load_dwordx4 v[124:127], v163, s[24:25] offset:512
	global_load_dwordx4 v[120:123], v163, s[24:25] offset:528
	v_lshlrev_b32_e32 v161, 1, v160
	v_lshlrev_b32_e32 v165, 2, v160
	s_and_b64 vcc, exec, s[0:1]
	s_mov_b64 s[0:1], -1
	s_mov_b64 s[98:99], s[6:7]
	global_load_dwordx4 v[172:175], v161, s[98:99]
	global_load_dwordx4 v[176:179], v161, s[98:99] offset:256
	s_add_u32 s98, s6, 0x8000
	s_addc_u32 s99, s7, 0
	global_load_dwordx4 v[180:183], v161, s[98:99]
	global_load_dwordx4 v[184:187], v161, s[98:99] offset:256
	s_add_u32 s98, s6, 0x10000
	s_addc_u32 s99, s7, 0
	global_load_dwordx4 v[188:191], v161, s[98:99]
	global_load_dwordx4 v[192:195], v161, s[98:99] offset:256
	s_add_u32 s98, s6, 0x18000
	s_addc_u32 s99, s7, 0
	global_load_dwordx4 v[196:199], v161, s[98:99]
	global_load_dwordx4 v[200:203], v161, s[98:99] offset:256
	s_add_u32 s98, s6, 0x40000
	s_addc_u32 s99, s7, 0
	global_load_dwordx4 v[204:207], v161, s[98:99]
	global_load_dwordx4 v[208:211], v161, s[98:99] offset:256
	s_add_u32 s98, s6, 0x48000
	s_addc_u32 s99, s7, 0
	global_load_dwordx4 v[212:215], v161, s[98:99]
	global_load_dwordx4 v[216:219], v161, s[98:99] offset:256
	s_add_u32 s98, s6, 0x50000
	s_addc_u32 s99, s7, 0
	global_load_dwordx4 v[220:223], v161, s[98:99]
	global_load_dwordx4 v[224:227], v161, s[98:99] offset:256
	s_add_u32 s98, s6, 0x58000
	s_addc_u32 s99, s7, 0
	global_load_dwordx4 v[228:231], v161, s[98:99]
	global_load_dwordx4 v[232:235], v161, s[98:99] offset:256
	s_waitcnt vmcnt(15)
	v_lshlrev_b32_e32 v236, 16, v172
	v_and_b32_e32 v237, 0xffff0000, v172
	v_lshlrev_b32_e32 v238, 16, v173
	v_and_b32_e32 v239, 0xffff0000, v173
	v_lshlrev_b32_e32 v240, 16, v174
	v_and_b32_e32 v241, 0xffff0000, v174
	v_lshlrev_b32_e32 v242, 16, v175
	v_and_b32_e32 v243, 0xffff0000, v175
	s_mov_b64 s[100:101], s[8:9]
	v_pk_fma_f32 v[140:141], v[140:141], v[132:133], v[236:237]
	v_pk_fma_f32 v[142:143], v[142:143], v[134:135], v[238:239]
	v_pk_fma_f32 v[136:137], v[136:137], v[128:129], v[240:241]
	v_pk_fma_f32 v[138:139], v[138:139], v[130:131], v[242:243]
	global_store_dwordx4 v165, v[140:143], s[100:101]
	global_store_dwordx4 v165, v[136:139], s[100:101] offset:16
	s_waitcnt vmcnt(16)
	v_lshlrev_b32_e32 v236, 16, v176
	v_and_b32_e32 v237, 0xffff0000, v176
	v_lshlrev_b32_e32 v238, 16, v177
	v_and_b32_e32 v239, 0xffff0000, v177
	v_lshlrev_b32_e32 v240, 16, v178
	v_and_b32_e32 v241, 0xffff0000, v178
	v_lshlrev_b32_e32 v242, 16, v179
	v_and_b32_e32 v243, 0xffff0000, v179
	v_pk_fma_f32 v[116:117], v[116:117], v[124:125], v[236:237]
	v_pk_fma_f32 v[118:119], v[118:119], v[126:127], v[238:239]
	v_pk_fma_f32 v[112:113], v[112:113], v[120:121], v[240:241]
	v_pk_fma_f32 v[114:115], v[114:115], v[122:123], v[242:243]
	global_store_dwordx4 v165, v[116:119], s[100:101] offset:512
	global_store_dwordx4 v165, v[112:115], s[100:101] offset:528
	s_waitcnt vmcnt(17)
	v_lshlrev_b32_e32 v236, 16, v180
	v_and_b32_e32 v237, 0xffff0000, v180
	v_lshlrev_b32_e32 v238, 16, v181
	v_and_b32_e32 v239, 0xffff0000, v181
	v_lshlrev_b32_e32 v240, 16, v182
	v_and_b32_e32 v241, 0xffff0000, v182
	v_lshlrev_b32_e32 v242, 16, v183
	v_and_b32_e32 v243, 0xffff0000, v183
	s_add_u32 s100, s8, 0x10000
	s_addc_u32 s101, s9, 0
	v_pk_fma_f32 v[108:109], v[108:109], v[132:133], v[236:237]
	v_pk_fma_f32 v[110:111], v[110:111], v[134:135], v[238:239]
	v_pk_fma_f32 v[104:105], v[104:105], v[128:129], v[240:241]
	v_pk_fma_f32 v[106:107], v[106:107], v[130:131], v[242:243]
	global_store_dwordx4 v165, v[108:111], s[100:101]
	global_store_dwordx4 v165, v[104:107], s[100:101] offset:16
	s_waitcnt vmcnt(18)
	v_lshlrev_b32_e32 v236, 16, v184
	v_and_b32_e32 v237, 0xffff0000, v184
	v_lshlrev_b32_e32 v238, 16, v185
	v_and_b32_e32 v239, 0xffff0000, v185
	v_lshlrev_b32_e32 v240, 16, v186
	v_and_b32_e32 v241, 0xffff0000, v186
	v_lshlrev_b32_e32 v242, 16, v187
	v_and_b32_e32 v243, 0xffff0000, v187
	v_pk_fma_f32 v[100:101], v[100:101], v[124:125], v[236:237]
	v_pk_fma_f32 v[102:103], v[102:103], v[126:127], v[238:239]
	v_pk_fma_f32 v[96:97], v[96:97], v[120:121], v[240:241]
	v_pk_fma_f32 v[98:99], v[98:99], v[122:123], v[242:243]
	global_store_dwordx4 v165, v[100:103], s[100:101] offset:512
	global_store_dwordx4 v165, v[96:99], s[100:101] offset:528
	s_waitcnt vmcnt(19)
	v_lshlrev_b32_e32 v236, 16, v188
	v_and_b32_e32 v237, 0xffff0000, v188
	v_lshlrev_b32_e32 v238, 16, v189
	v_and_b32_e32 v239, 0xffff0000, v189
	v_lshlrev_b32_e32 v240, 16, v190
	v_and_b32_e32 v241, 0xffff0000, v190
	v_lshlrev_b32_e32 v242, 16, v191
	v_and_b32_e32 v243, 0xffff0000, v191
	s_add_u32 s100, s8, 0x20000
	s_addc_u32 s101, s9, 0
	v_pk_fma_f32 v[92:93], v[92:93], v[132:133], v[236:237]
	v_pk_fma_f32 v[94:95], v[94:95], v[134:135], v[238:239]
	v_pk_fma_f32 v[88:89], v[88:89], v[128:129], v[240:241]
	v_pk_fma_f32 v[90:91], v[90:91], v[130:131], v[242:243]
	global_store_dwordx4 v165, v[92:95], s[100:101]
	global_store_dwordx4 v165, v[88:91], s[100:101] offset:16
	s_waitcnt vmcnt(20)
;     __device__ __forceinline__ void operator()(const f32x4 (&acc)[2][2][4][2], const Unit& u, int wr, int wc, int fr, int fq) const {
;     ...
;         for (int ai = 0; ai < 2; ++ai)
; #pragma unroll
;             for (int m = 0; m < 4; ++m) { const int row = row0 + 128 * ai + 16 * m;
; #pragma unroll
;                 for (int bj = 0; bj < 2; ++bj) { const size_t off = (size_t)row * DM + col0 + 128 * bj;
;                     const u32x4 w = *(const u32x4*)(x1b + off);
;                     const f32x4 x0 = (f32x4){__uint_as_float(w.x << 16), __uint_as_float(w.x & 0xffff0000u), __uint_as_float(w.y << 16), __uint_as_float(w.y & 0xffff0000u)};
;                     const f32x4 x1 = (f32x4){__uint_as_float(w.z << 16), __uint_as_float(w.z & 0xffff0000u), __uint_as_float(w.w << 16), __uint_as_float(w.w & 0xffff0000u)};
;                     *(f32x4*)(out + off) = x0 + g[bj][0] * acc[ai][bj][m][0]; *(f32x4*)(out + off + 4) = x1 + g[bj][1] * acc[ai][bj][m][1]; } }
	v_lshlrev_b32_e32 v236, 16, v192
	v_and_b32_e32 v237, 0xffff0000, v192
	v_lshlrev_b32_e32 v238, 16, v193
	v_and_b32_e32 v239, 0xffff0000, v193
	v_lshlrev_b32_e32 v240, 16, v194
	v_and_b32_e32 v241, 0xffff0000, v194
	v_lshlrev_b32_e32 v242, 16, v195
	v_and_b32_e32 v243, 0xffff0000, v195
	v_pk_fma_f32 v[84:85], v[84:85], v[124:125], v[236:237]
	v_pk_fma_f32 v[86:87], v[86:87], v[126:127], v[238:239]
	v_pk_fma_f32 v[80:81], v[80:81], v[120:121], v[240:241]
	v_pk_fma_f32 v[82:83], v[82:83], v[122:123], v[242:243]
	global_store_dwordx4 v165, v[84:87], s[100:101] offset:512
	global_store_dwordx4 v165, v[80:83], s[100:101] offset:528
	s_waitcnt vmcnt(21)
	v_lshlrev_b32_e32 v236, 16, v196
	v_and_b32_e32 v237, 0xffff0000, v196
	v_lshlrev_b32_e32 v238, 16, v197
	v_and_b32_e32 v239, 0xffff0000, v197
	v_lshlrev_b32_e32 v240, 16, v198
	v_and_b32_e32 v241, 0xffff0000, v198
	v_lshlrev_b32_e32 v242, 16, v199
	v_and_b32_e32 v243, 0xffff0000, v199
	s_add_u32 s100, s8, 0x30000
	s_addc_u32 s101, s9, 0
	v_pk_fma_f32 v[76:77], v[76:77], v[132:133], v[236:237]
	v_pk_fma_f32 v[78:79], v[78:79], v[134:135], v[238:239]
	v_pk_fma_f32 v[72:73], v[72:73], v[128:129], v[240:241]
	v_pk_fma_f32 v[74:75], v[74:75], v[130:131], v[242:243]
	global_store_dwordx4 v165, v[76:79], s[100:101]
	global_store_dwordx4 v165, v[72:75], s[100:101] offset:16
	s_waitcnt vmcnt(22)
	v_lshlrev_b32_e32 v236, 16, v200
	v_and_b32_e32 v237, 0xffff0000, v200
	v_lshlrev_b32_e32 v238, 16, v201
	v_and_b32_e32 v239, 0xffff0000, v201
	v_lshlrev_b32_e32 v240, 16, v202
	v_and_b32_e32 v241, 0xffff0000, v202
	v_lshlrev_b32_e32 v242, 16, v203
	v_and_b32_e32 v243, 0xffff0000, v203
	v_pk_fma_f32 v[68:69], v[68:69], v[124:125], v[236:237]
	v_pk_fma_f32 v[70:71], v[70:71], v[126:127], v[238:239]
	v_pk_fma_f32 v[64:65], v[64:65], v[120:121], v[240:241]
	v_pk_fma_f32 v[66:67], v[66:67], v[122:123], v[242:243]
	global_store_dwordx4 v165, v[68:71], s[100:101] offset:512
	global_store_dwordx4 v165, v[64:67], s[100:101] offset:528
	s_waitcnt vmcnt(23)
	v_lshlrev_b32_e32 v236, 16, v204
	v_and_b32_e32 v237, 0xffff0000, v204
	v_lshlrev_b32_e32 v238, 16, v205
	v_and_b32_e32 v239, 0xffff0000, v205
	v_lshlrev_b32_e32 v240, 16, v206
	v_and_b32_e32 v241, 0xffff0000, v206
	v_lshlrev_b32_e32 v242, 16, v207
	v_and_b32_e32 v243, 0xffff0000, v207
	s_add_u32 s100, s8, 0x80000
	s_addc_u32 s101, s9, 0
	v_pk_fma_f32 v[60:61], v[60:61], v[132:133], v[236:237]
	v_pk_fma_f32 v[62:63], v[62:63], v[134:135], v[238:239]
	v_pk_fma_f32 v[56:57], v[56:57], v[128:129], v[240:241]
	v_pk_fma_f32 v[58:59], v[58:59], v[130:131], v[242:243]
	global_store_dwordx4 v165, v[60:63], s[100:101]
	global_store_dwordx4 v165, v[56:59], s[100:101] offset:16
	s_waitcnt vmcnt(24)
	v_lshlrev_b32_e32 v236, 16, v208
	v_and_b32_e32 v237, 0xffff0000, v208
	v_lshlrev_b32_e32 v238, 16, v209
	v_and_b32_e32 v239, 0xffff0000, v209
	v_lshlrev_b32_e32 v240, 16, v210
	v_and_b32_e32 v241, 0xffff0000, v210
	v_lshlrev_b32_e32 v242, 16, v211
	v_and_b32_e32 v243, 0xffff0000, v211
	v_pk_fma_f32 v[52:53], v[52:53], v[124:125], v[236:237]
	v_pk_fma_f32 v[54:55], v[54:55], v[126:127], v[238:239]
	v_pk_fma_f32 v[48:49], v[48:49], v[120:121], v[240:241]
	v_pk_fma_f32 v[50:51], v[50:51], v[122:123], v[242:243]
	global_store_dwordx4 v165, v[52:55], s[100:101] offset:512
	global_store_dwordx4 v165, v[48:51], s[100:101] offset:528
	s_waitcnt vmcnt(25)
	v_lshlrev_b32_e32 v236, 16, v212
	v_and_b32_e32 v237, 0xffff0000, v212
	v_lshlrev_b32_e32 v238, 16, v213
	v_and_b32_e32 v239, 0xffff0000, v213
	v_lshlrev_b32_e32 v240, 16, v214
	v_and_b32_e32 v241, 0xffff0000, v214
	v_lshlrev_b32_e32 v242, 16, v215
	v_and_b32_e32 v243, 0xffff0000, v215
	s_add_u32 s100, s8, 0x90000
	s_addc_u32 s101, s9, 0
	v_pk_fma_f32 v[44:45], v[44:45], v[132:133], v[236:237]
	v_pk_fma_f32 v[46:47], v[46:47], v[134:135], v[238:239]
	v_pk_fma_f32 v[40:41], v[40:41], v[128:129], v[240:241]
	v_pk_fma_f32 v[42:43], v[42:43], v[130:131], v[242:243]
	global_store_dwordx4 v165, v[44:47], s[100:101]
	global_store_dwordx4 v165, v[40:43], s[100:101] offset:16
	s_waitcnt vmcnt(26)
;     __device__ __forceinline__ void operator()(const f32x4 (&acc)[2][2][4][2], const Unit& u, int wr, int wc, int fr, int fq) const {
;     ...
;         for (int ai = 0; ai < 2; ++ai)
; #pragma unroll
;             for (int m = 0; m < 4; ++m) { const int row = row0 + 128 * ai + 16 * m;
; #pragma unroll
;                 for (int bj = 0; bj < 2; ++bj) { const size_t off = (size_t)row * DM + col0 + 128 * bj;
;                     const u32x4 w = *(const u32x4*)(x1b + off);
;                     const f32x4 x0 = (f32x4){__uint_as_float(w.x << 16), __uint_as_float(w.x & 0xffff0000u), __uint_as_float(w.y << 16), __uint_as_float(w.y & 0xffff0000u)};
;                     const f32x4 x1 = (f32x4){__uint_as_float(w.z << 16), __uint_as_float(w.z & 0xffff0000u), __uint_as_float(w.w << 16), __uint_as_float(w.w & 0xffff0000u)};
;                     *(f32x4*)(out + off) = x0 + g[bj][0] * acc[ai][bj][m][0]; *(f32x4*)(out + off + 4) = x1 + g[bj][1] * acc[ai][bj][m][1]; } }
	v_lshlrev_b32_e32 v236, 16, v216
	v_and_b32_e32 v237, 0xffff0000, v216
	v_lshlrev_b32_e32 v238, 16, v217
	v_and_b32_e32 v239, 0xffff0000, v217
	v_lshlrev_b32_e32 v240, 16, v218
	v_and_b32_e32 v241, 0xffff0000, v218
	v_lshlrev_b32_e32 v242, 16, v219
	v_and_b32_e32 v243, 0xffff0000, v219
	v_pk_fma_f32 v[36:37], v[36:37], v[124:125], v[236:237]
	v_pk_fma_f32 v[38:39], v[38:39], v[126:127], v[238:239]
	v_pk_fma_f32 v[32:33], v[32:33], v[120:121], v[240:241]
	v_pk_fma_f32 v[34:35], v[34:35], v[122:123], v[242:243]
	global_store_dwordx4 v165, v[36:39], s[100:101] offset:512
	global_store_dwordx4 v165, v[32:35], s[100:101] offset:528
	s_waitcnt vmcnt(27)
	v_lshlrev_b32_e32 v236, 16, v220
	v_and_b32_e32 v237, 0xffff0000, v220
	v_lshlrev_b32_e32 v238, 16, v221
	v_and_b32_e32 v239, 0xffff0000, v221
	v_lshlrev_b32_e32 v240, 16, v222
	v_and_b32_e32 v241, 0xffff0000, v222
	v_lshlrev_b32_e32 v242, 16, v223
	v_and_b32_e32 v243, 0xffff0000, v223
	s_add_u32 s100, s8, 0xa0000
	s_addc_u32 s101, s9, 0
	v_pk_fma_f32 v[28:29], v[28:29], v[132:133], v[236:237]
	v_pk_fma_f32 v[30:31], v[30:31], v[134:135], v[238:239]
	v_pk_fma_f32 v[24:25], v[24:25], v[128:129], v[240:241]
	v_pk_fma_f32 v[26:27], v[26:27], v[130:131], v[242:243]
	global_store_dwordx4 v165, v[28:31], s[100:101]
	global_store_dwordx4 v165, v[24:27], s[100:101] offset:16
	s_waitcnt vmcnt(28)
	v_lshlrev_b32_e32 v236, 16, v224
	v_and_b32_e32 v237, 0xffff0000, v224
	v_lshlrev_b32_e32 v238, 16, v225
	v_and_b32_e32 v239, 0xffff0000, v225
	v_lshlrev_b32_e32 v240, 16, v226
	v_and_b32_e32 v241, 0xffff0000, v226
	v_lshlrev_b32_e32 v242, 16, v227
	v_and_b32_e32 v243, 0xffff0000, v227
	v_pk_fma_f32 v[20:21], v[20:21], v[124:125], v[236:237]
	v_pk_fma_f32 v[22:23], v[22:23], v[126:127], v[238:239]
	v_pk_fma_f32 v[16:17], v[16:17], v[120:121], v[240:241]
	v_pk_fma_f32 v[18:19], v[18:19], v[122:123], v[242:243]
	global_store_dwordx4 v165, v[20:23], s[100:101] offset:512
	global_store_dwordx4 v165, v[16:19], s[100:101] offset:528
	s_waitcnt vmcnt(29)
	v_lshlrev_b32_e32 v236, 16, v228
	v_and_b32_e32 v237, 0xffff0000, v228
	v_lshlrev_b32_e32 v238, 16, v229
	v_and_b32_e32 v239, 0xffff0000, v229
	v_lshlrev_b32_e32 v240, 16, v230
	v_and_b32_e32 v241, 0xffff0000, v230
	v_lshlrev_b32_e32 v242, 16, v231
	v_and_b32_e32 v243, 0xffff0000, v231
	s_add_u32 s100, s8, 0xb0000
	s_addc_u32 s101, s9, 0
	v_pk_fma_f32 v[12:13], v[12:13], v[132:133], v[236:237]
	v_pk_fma_f32 v[14:15], v[14:15], v[134:135], v[238:239]
	v_pk_fma_f32 v[8:9], v[8:9], v[128:129], v[240:241]
	v_pk_fma_f32 v[10:11], v[10:11], v[130:131], v[242:243]
	global_store_dwordx4 v165, v[12:15], s[100:101]
	global_store_dwordx4 v165, v[8:11], s[100:101] offset:16
	s_waitcnt vmcnt(30)
	v_lshlrev_b32_e32 v236, 16, v232
	v_and_b32_e32 v237, 0xffff0000, v232
	v_lshlrev_b32_e32 v238, 16, v233
	v_and_b32_e32 v239, 0xffff0000, v233
	v_lshlrev_b32_e32 v240, 16, v234
	v_and_b32_e32 v241, 0xffff0000, v234
	v_lshlrev_b32_e32 v242, 16, v235
	v_and_b32_e32 v243, 0xffff0000, v235
	v_pk_fma_f32 v[4:5], v[4:5], v[124:125], v[236:237]
	v_pk_fma_f32 v[6:7], v[6:7], v[126:127], v[238:239]
	v_pk_fma_f32 v[0:1], v[0:1], v[120:121], v[240:241]
	v_pk_fma_f32 v[2:3], v[2:3], v[122:123], v[242:243]
	global_store_dwordx4 v165, v[4:7], s[100:101] offset:512
	global_store_dwordx4 v165, v[0:3], s[100:101] offset:528
	s_cbranch_vccnz .LBB0_1063
	s_andn2_b64 vcc, exec, s[2:3]
	s_cbranch_vccnz .LBB0_1062
	s_barrier
	s_branch .LBB0_1062

; #define LAS __attribute__((address_space(3)))
; __global__ void __launch_bounds__(512, 2) hybrid_block_fwd(Params p_unused) {
;     extern __shared__ __attribute__((aligned(16))) unsigned char lds_raw[];
;     LAS unsigned char* lds = (LAS unsigned char*)lds_raw;
	.amdhsa_kernel _Z16hybrid_block_fwd6Params
		.amdhsa_group_segment_fixed_size 0
		.amdhsa_private_segment_fixed_size 0
		.amdhsa_kernarg_size 424
		.amdhsa_user_sgpr_count 2
		.amdhsa_user_sgpr_dispatch_ptr 0
		.amdhsa_user_sgpr_queue_ptr 0
		.amdhsa_user_sgpr_kernarg_segment_ptr 1
		.amdhsa_user_sgpr_dispatch_id 0
		.amdhsa_user_sgpr_kernarg_preload_length 0
		.amdhsa_user_sgpr_kernarg_preload_offset 0
		.amdhsa_user_sgpr_private_segment_size 0
		.amdhsa_uses_dynamic_stack 0
		.amdhsa_enable_private_segment 0
		.amdhsa_system_sgpr_workgroup_id_x 1
		.amdhsa_system_sgpr_workgroup_id_y 0
		.amdhsa_system_sgpr_workgroup_id_z 0
		.amdhsa_system_sgpr_workgroup_info 0
		.amdhsa_system_vgpr_workitem_id 2
		.amdhsa_next_free_vgpr 248
		.amdhsa_next_free_sgpr 102
		.amdhsa_accum_offset 248
		.amdhsa_reserve_vcc 1
		.amdhsa_float_round_mode_32 0
		.amdhsa_float_round_mode_16_64 0
		.amdhsa_float_denorm_mode_32 3
		.amdhsa_float_denorm_mode_16_64 3
		.amdhsa_dx10_clamp 1
		.amdhsa_ieee_mode 1
		.amdhsa_fp16_overflow 0
		.amdhsa_tg_split 0
		.amdhsa_exception_fp_ieee_invalid_op 0
		.amdhsa_exception_fp_denorm_src 0
		.amdhsa_exception_fp_ieee_div_zero 0
		.amdhsa_exception_fp_ieee_overflow 0
		.amdhsa_exception_fp_ieee_underflow 0
		.amdhsa_exception_fp_ieee_inexact 0
		.amdhsa_exception_int_div_zero 0
	.end_amdhsa_kernel

; __global__ void __launch_bounds__(512, 2) hybrid_block_fwd(Params p_unused) {
;     extern __shared__ __attribute__((aligned(16))) unsigned char lds_raw[];
amdhsa.kernels:
  - .agpr_count:     0
    .args:
      - .offset:         0
        .size:           168
        .value_kind:     by_value
      - .offset:         168
        .size:           4
        .value_kind:     hidden_block_count_x
      - .offset:         172
        .size:           4
        .value_kind:     hidden_block_count_y
      - .offset:         176
        .size:           4
        .value_kind:     hidden_block_count_z
      - .offset:         180
        .size:           2
        .value_kind:     hidden_group_size_x
      - .offset:         182
        .size:           2
        .value_kind:     hidden_group_size_y
      - .offset:         184
        .size:           2
        .value_kind:     hidden_group_size_z
      - .offset:         186
        .size:           2
        .value_kind:     hidden_remainder_x
      - .offset:         188
        .size:           2
        .value_kind:     hidden_remainder_y
      - .offset:         190
        .size:           2
        .value_kind:     hidden_remainder_z
      - .offset:         208
        .size:           8
        .value_kind:     hidden_global_offset_x
      - .offset:         216
        .size:           8
        .value_kind:     hidden_global_offset_y
      - .offset:         224
        .size:           8
        .value_kind:     hidden_global_offset_z
      - .offset:         232
        .size:           2
        .value_kind:     hidden_grid_dims
      - .offset:         256
        .size:           8
        .value_kind:     hidden_multigrid_sync_arg
      - .offset:         288
        .size:           4
        .value_kind:     hidden_dynamic_lds_size
    .group_segment_fixed_size: 0
    .kernarg_segment_align: 8
    .kernarg_segment_size: 424
    .language:       OpenCL C
    .language_version:
      - 2
      - 0
    .max_flat_workgroup_size: 512
    .name:           _Z16hybrid_block_fwd6Params
    .private_segment_fixed_size: 0
    .sgpr_count:     108
    .sgpr_spill_count: 95
    .symbol:         _Z16hybrid_block_fwd6Params.kd
    .uniform_work_group_size: 1
    .uses_dynamic_stack: false
    .vgpr_count:     248
    .vgpr_spill_count: 0
    .wavefront_size: 64
